# grid barrier: generation index taken from the barrier's position in the kernel (each seam runs once per launch) instead of an integer division of the arrival count; workgroup 0 init publishes with one
# speedup vs baseline: 1.0113x; 1.0113x over previous
; __global__ void __launch_bounds__(512, 2) fwd_megakernel(Params p) {
;     ...
;         if (blockIdx.x == 0) {
;             for (int i = threadIdx.x; i < 16384 - 64; i += 512) barw[i] = 0u;
;             __threadfence(); __syncthreads();
;             if (threadIdx.x == 0) { asm volatile("s_waitcnt vmcnt(0)" ::: "memory"); __hip_atomic_store(flag, MAGIC, __ATOMIC_RELEASE, __HIP_MEMORY_SCOPE_AGENT); }
;         } else if (threadIdx.x == 0) {
;             unsigned sp = 0; while (__hip_atomic_load(flag, __ATOMIC_RELAXED, __HIP_MEMORY_SCOPE_AGENT) != MAGIC) { __builtin_amdgcn_s_sleep(1); if (++sp > (1u << 22)) break; }
;             __builtin_amdgcn_fence(__ATOMIC_ACQUIRE, "agent");
;         }
;         __syncthreads();
.LBB0_32:
	s_or_b64 exec, exec, s[4:5]
	v_cmp_eq_u32_e32 vcc, 0, v152
	s_waitcnt vmcnt(0) lgkmcnt(0)
	s_barrier
	s_and_saveexec_b64 s[4:5], vcc
	s_cbranch_execz .LBB0_34
	v_mov_b32_e32 v0, 0
	v_mov_b32_e32 v1, 0x600df1a6
	buffer_wbl2 sc1
	s_waitcnt vmcnt(0)
	global_store_dword v0, v1, s[26:27] sc1

; __device__ __forceinline__ unsigned xb_ld(unsigned* p)              { return __hip_atomic_load(p, __ATOMIC_RELAXED, __HIP_MEMORY_SCOPE_AGENT); }
; __device__ __forceinline__ unsigned xb_add(unsigned* p, unsigned v) { return __hip_atomic_fetch_add(p, v, __ATOMIC_RELAXED, __HIP_MEMORY_SCOPE_AGENT); }
; #define XB_SPIN(cond, bar) do { unsigned _sp = 0; while (cond) { __builtin_amdgcn_s_sleep(1); \
;     if ((++_sp & 255u) == 0u) { if (xb_ld(&(bar)[XB_TMO])) break; if (_sp > XB_SPIN_CAP) { atomicAdd(&(bar)[XB_TMO], 1u); break; } } } } while (0)
; __device__ __forceinline__ void xcd_barrier(const XcdBarrier& b) {
;     ...
;         unsigned nloc = b.st[0], nx = b.st[1];
;         if (nloc == 0u) { xcd_barrier_complete(bar, b.x, nloc, nx); b.st[0] = nloc; b.st[1] = nx; }
;         const unsigned old = xb_add(&bar[XB_XSUB(b.x)], 1u);
;         const unsigned gen = old / nloc;
;         if (old + 1u == (gen + 1u) * nloc) {
;             __builtin_amdgcn_fence(__ATOMIC_RELEASE, "agent");
;             asm volatile("s_waitcnt vmcnt(0)" ::: "memory");
;             const unsigned og = xb_add(&bar[XB_TOP], 1u);
;             const unsigned tg = og / nx;
;             if (og + 1u == (tg + 1u) * nx) xb_add(&bar[XB_TOPGEN], 1u);
;             else XB_SPIN(xb_ld(&bar[XB_TOPGEN]) == tg, bar);
;             __builtin_amdgcn_fence(__ATOMIC_ACQUIRE, "agent");
;             xb_add(&bar[XB_XGEN(b.x)], 1u);
;             asm volatile("s_waitcnt vmcnt(0)" ::: "memory");
;         } else {
;             XB_SPIN(xb_ld(&bar[XB_XGEN(b.x)]) == gen, bar);
.LBB0_81:
	s_or_b64 exec, exec, s[8:9]
	s_waitcnt vmcnt(0) lgkmcnt(0)
	v_readfirstlane_b32 s2, v3
	v_mul_u32_u24_e32 v4, 1, v2
	v_mul_u32_u24_e32 v5, 1, v0
	s_add_u32 s2, s2, 1
	v_cmp_ne_u32_e32 vcc, s2, v4
	v_mov_b32_e32 v2, 0x583000
	v_readfirstlane_b32 s8, v5
	s_cbranch_vccnz .Lgb_poll_0
	buffer_wbl2 sc1
	v_mov_b32_e32 v3, 1
	s_waitcnt vmcnt(0)
	global_atomic_add v2, v3, s[72:73] offset:1024

; __device__ __forceinline__ unsigned xb_ld(unsigned* p)              { return __hip_atomic_load(p, __ATOMIC_RELAXED, __HIP_MEMORY_SCOPE_AGENT); }
; __device__ __forceinline__ unsigned xb_add(unsigned* p, unsigned v) { return __hip_atomic_fetch_add(p, v, __ATOMIC_RELAXED, __HIP_MEMORY_SCOPE_AGENT); }
; #define XB_SPIN(cond, bar) do { unsigned _sp = 0; while (cond) { __builtin_amdgcn_s_sleep(1); \
;     if ((++_sp & 255u) == 0u) { if (xb_ld(&(bar)[XB_TMO])) break; if (_sp > XB_SPIN_CAP) { atomicAdd(&(bar)[XB_TMO], 1u); break; } } } } while (0)
; __device__ __forceinline__ void xcd_barrier(const XcdBarrier& b) {
;     ...
;         unsigned nloc = b.st[0], nx = b.st[1];
;         if (nloc == 0u) { xcd_barrier_complete(bar, b.x, nloc, nx); b.st[0] = nloc; b.st[1] = nx; }
;         const unsigned old = xb_add(&bar[XB_XSUB(b.x)], 1u);
;         const unsigned gen = old / nloc;
;         if (old + 1u == (gen + 1u) * nloc) {
;             __builtin_amdgcn_fence(__ATOMIC_RELEASE, "agent");
;             asm volatile("s_waitcnt vmcnt(0)" ::: "memory");
;             const unsigned og = xb_add(&bar[XB_TOP], 1u);
;             const unsigned tg = og / nx;
;             if (og + 1u == (tg + 1u) * nx) xb_add(&bar[XB_TOPGEN], 1u);
;             else XB_SPIN(xb_ld(&bar[XB_TOPGEN]) == tg, bar);
;             __builtin_amdgcn_fence(__ATOMIC_ACQUIRE, "agent");
;             xb_add(&bar[XB_XGEN(b.x)], 1u);
;             asm volatile("s_waitcnt vmcnt(0)" ::: "memory");
;         } else {
;             XB_SPIN(xb_ld(&bar[XB_XGEN(b.x)]) == gen, bar);
.LBB0_314:
	s_or_b64 exec, exec, s[8:9]
	s_waitcnt vmcnt(0) lgkmcnt(0)
	v_readfirstlane_b32 s2, v3
	v_mul_u32_u24_e32 v4, 2, v2
	v_mul_u32_u24_e32 v5, 2, v0
	s_add_u32 s2, s2, 1
	v_cmp_ne_u32_e32 vcc, s2, v4
	v_mov_b32_e32 v2, 0x583000
	v_readfirstlane_b32 s8, v5
	s_cbranch_vccnz .Lgb_poll_1
	buffer_wbl2 sc1
	v_mov_b32_e32 v3, 1
	s_waitcnt vmcnt(0)
	global_atomic_add v2, v3, s[72:73] offset:1024

; __device__ __forceinline__ unsigned xb_ld(unsigned* p)              { return __hip_atomic_load(p, __ATOMIC_RELAXED, __HIP_MEMORY_SCOPE_AGENT); }
; __device__ __forceinline__ unsigned xb_add(unsigned* p, unsigned v) { return __hip_atomic_fetch_add(p, v, __ATOMIC_RELAXED, __HIP_MEMORY_SCOPE_AGENT); }
; #define XB_SPIN(cond, bar) do { unsigned _sp = 0; while (cond) { __builtin_amdgcn_s_sleep(1); \
;     if ((++_sp & 255u) == 0u) { if (xb_ld(&(bar)[XB_TMO])) break; if (_sp > XB_SPIN_CAP) { atomicAdd(&(bar)[XB_TMO], 1u); break; } } } } while (0)
; __device__ __forceinline__ void xcd_barrier(const XcdBarrier& b) {
;     ...
;         unsigned nloc = b.st[0], nx = b.st[1];
;         if (nloc == 0u) { xcd_barrier_complete(bar, b.x, nloc, nx); b.st[0] = nloc; b.st[1] = nx; }
;         const unsigned old = xb_add(&bar[XB_XSUB(b.x)], 1u);
;         const unsigned gen = old / nloc;
;         if (old + 1u == (gen + 1u) * nloc) {
;             __builtin_amdgcn_fence(__ATOMIC_RELEASE, "agent");
;             asm volatile("s_waitcnt vmcnt(0)" ::: "memory");
;             const unsigned og = xb_add(&bar[XB_TOP], 1u);
;             const unsigned tg = og / nx;
;             if (og + 1u == (tg + 1u) * nx) xb_add(&bar[XB_TOPGEN], 1u);
;             else XB_SPIN(xb_ld(&bar[XB_TOPGEN]) == tg, bar);
;             __builtin_amdgcn_fence(__ATOMIC_ACQUIRE, "agent");
;             xb_add(&bar[XB_XGEN(b.x)], 1u);
;             asm volatile("s_waitcnt vmcnt(0)" ::: "memory");
;         } else {
;             XB_SPIN(xb_ld(&bar[XB_XGEN(b.x)]) == gen, bar);
.LBB0_413:
	s_or_b64 exec, exec, s[8:9]
	s_waitcnt vmcnt(0) lgkmcnt(0)
	v_readfirstlane_b32 s2, v3
	v_mul_u32_u24_e32 v4, 3, v2
	v_mul_u32_u24_e32 v5, 3, v0
	s_add_u32 s2, s2, 1
	v_cmp_ne_u32_e32 vcc, s2, v4
	v_mov_b32_e32 v2, 0x583000
	v_readfirstlane_b32 s8, v5
	s_cbranch_vccnz .Lgb_poll_2
	buffer_wbl2 sc1
	v_mov_b32_e32 v3, 1
	s_waitcnt vmcnt(0)
	global_atomic_add v2, v3, s[72:73] offset:1024

; __device__ __forceinline__ unsigned xb_ld(unsigned* p)              { return __hip_atomic_load(p, __ATOMIC_RELAXED, __HIP_MEMORY_SCOPE_AGENT); }
; __device__ __forceinline__ unsigned xb_add(unsigned* p, unsigned v) { return __hip_atomic_fetch_add(p, v, __ATOMIC_RELAXED, __HIP_MEMORY_SCOPE_AGENT); }
; #define XB_SPIN(cond, bar) do { unsigned _sp = 0; while (cond) { __builtin_amdgcn_s_sleep(1); \
;     if ((++_sp & 255u) == 0u) { if (xb_ld(&(bar)[XB_TMO])) break; if (_sp > XB_SPIN_CAP) { atomicAdd(&(bar)[XB_TMO], 1u); break; } } } } while (0)
; __device__ __forceinline__ void xcd_barrier(const XcdBarrier& b) {
;     ...
;         unsigned nloc = b.st[0], nx = b.st[1];
;         if (nloc == 0u) { xcd_barrier_complete(bar, b.x, nloc, nx); b.st[0] = nloc; b.st[1] = nx; }
;         const unsigned old = xb_add(&bar[XB_XSUB(b.x)], 1u);
;         const unsigned gen = old / nloc;
;         if (old + 1u == (gen + 1u) * nloc) {
;             __builtin_amdgcn_fence(__ATOMIC_RELEASE, "agent");
;             asm volatile("s_waitcnt vmcnt(0)" ::: "memory");
;             const unsigned og = xb_add(&bar[XB_TOP], 1u);
;             const unsigned tg = og / nx;
;             if (og + 1u == (tg + 1u) * nx) xb_add(&bar[XB_TOPGEN], 1u);
;             else XB_SPIN(xb_ld(&bar[XB_TOPGEN]) == tg, bar);
;             __builtin_amdgcn_fence(__ATOMIC_ACQUIRE, "agent");
;             xb_add(&bar[XB_XGEN(b.x)], 1u);
;             asm volatile("s_waitcnt vmcnt(0)" ::: "memory");
;         } else {
;             XB_SPIN(xb_ld(&bar[XB_XGEN(b.x)]) == gen, bar);
.LBB0_573:
	s_or_b64 exec, exec, s[8:9]
	s_waitcnt vmcnt(0) lgkmcnt(0)
	v_readfirstlane_b32 s2, v3
	v_mul_u32_u24_e32 v4, 4, v2
	v_mul_u32_u24_e32 v5, 4, v0
	s_add_u32 s2, s2, 1
	v_cmp_ne_u32_e32 vcc, s2, v4
	v_mov_b32_e32 v2, 0x583000
	v_readfirstlane_b32 s8, v5
	s_cbranch_vccnz .Lgb_poll_3
	buffer_wbl2 sc1
	v_mov_b32_e32 v3, 1
	s_waitcnt vmcnt(0)
	global_atomic_add v2, v3, s[72:73] offset:1024

; __device__ __forceinline__ unsigned xb_ld(unsigned* p)              { return __hip_atomic_load(p, __ATOMIC_RELAXED, __HIP_MEMORY_SCOPE_AGENT); }
; __device__ __forceinline__ unsigned xb_add(unsigned* p, unsigned v) { return __hip_atomic_fetch_add(p, v, __ATOMIC_RELAXED, __HIP_MEMORY_SCOPE_AGENT); }
; #define XB_SPIN(cond, bar) do { unsigned _sp = 0; while (cond) { __builtin_amdgcn_s_sleep(1); \
;     if ((++_sp & 255u) == 0u) { if (xb_ld(&(bar)[XB_TMO])) break; if (_sp > XB_SPIN_CAP) { atomicAdd(&(bar)[XB_TMO], 1u); break; } } } } while (0)
; __device__ __forceinline__ void xcd_barrier(const XcdBarrier& b) {
;     ...
;         unsigned nloc = b.st[0], nx = b.st[1];
;         if (nloc == 0u) { xcd_barrier_complete(bar, b.x, nloc, nx); b.st[0] = nloc; b.st[1] = nx; }
;         const unsigned old = xb_add(&bar[XB_XSUB(b.x)], 1u);
;         const unsigned gen = old / nloc;
;         if (old + 1u == (gen + 1u) * nloc) {
;             __builtin_amdgcn_fence(__ATOMIC_RELEASE, "agent");
;             asm volatile("s_waitcnt vmcnt(0)" ::: "memory");
;             const unsigned og = xb_add(&bar[XB_TOP], 1u);
;             const unsigned tg = og / nx;
;             if (og + 1u == (tg + 1u) * nx) xb_add(&bar[XB_TOPGEN], 1u);
;             else XB_SPIN(xb_ld(&bar[XB_TOPGEN]) == tg, bar);
;             __builtin_amdgcn_fence(__ATOMIC_ACQUIRE, "agent");
;             xb_add(&bar[XB_XGEN(b.x)], 1u);
;             asm volatile("s_waitcnt vmcnt(0)" ::: "memory");
;         } else {
;             XB_SPIN(xb_ld(&bar[XB_XGEN(b.x)]) == gen, bar);
.LBB0_995:
	s_or_b64 exec, exec, s[8:9]
	s_waitcnt vmcnt(0) lgkmcnt(0)
	v_readfirstlane_b32 s2, v3
	v_mul_u32_u24_e32 v4, 5, v2
	v_mul_u32_u24_e32 v5, 5, v0
	s_add_u32 s2, s2, 1
	v_cmp_ne_u32_e32 vcc, s2, v4
	v_mov_b32_e32 v2, 0x583000
	v_readfirstlane_b32 s8, v5
	s_cbranch_vccnz .Lgb_poll_4
	buffer_wbl2 sc1
	v_mov_b32_e32 v3, 1
	s_waitcnt vmcnt(0)
	global_atomic_add v2, v3, s[72:73] offset:1024

; __device__ __forceinline__ unsigned xb_ld(unsigned* p)              { return __hip_atomic_load(p, __ATOMIC_RELAXED, __HIP_MEMORY_SCOPE_AGENT); }
; __device__ __forceinline__ unsigned xb_add(unsigned* p, unsigned v) { return __hip_atomic_fetch_add(p, v, __ATOMIC_RELAXED, __HIP_MEMORY_SCOPE_AGENT); }
; #define XB_SPIN(cond, bar) do { unsigned _sp = 0; while (cond) { __builtin_amdgcn_s_sleep(1); \
;     if ((++_sp & 255u) == 0u) { if (xb_ld(&(bar)[XB_TMO])) break; if (_sp > XB_SPIN_CAP) { atomicAdd(&(bar)[XB_TMO], 1u); break; } } } } while (0)
; __device__ __forceinline__ void xcd_barrier(const XcdBarrier& b) {
;     ...
;         unsigned nloc = b.st[0], nx = b.st[1];
;         if (nloc == 0u) { xcd_barrier_complete(bar, b.x, nloc, nx); b.st[0] = nloc; b.st[1] = nx; }
;         const unsigned old = xb_add(&bar[XB_XSUB(b.x)], 1u);
;         const unsigned gen = old / nloc;
;         if (old + 1u == (gen + 1u) * nloc) {
;             __builtin_amdgcn_fence(__ATOMIC_RELEASE, "agent");
;             asm volatile("s_waitcnt vmcnt(0)" ::: "memory");
;             const unsigned og = xb_add(&bar[XB_TOP], 1u);
;             const unsigned tg = og / nx;
;             if (og + 1u == (tg + 1u) * nx) xb_add(&bar[XB_TOPGEN], 1u);
;             else XB_SPIN(xb_ld(&bar[XB_TOPGEN]) == tg, bar);
;             __builtin_amdgcn_fence(__ATOMIC_ACQUIRE, "agent");
;             xb_add(&bar[XB_XGEN(b.x)], 1u);
;             asm volatile("s_waitcnt vmcnt(0)" ::: "memory");
;         } else {
;             XB_SPIN(xb_ld(&bar[XB_XGEN(b.x)]) == gen, bar);
.LBB0_1080:
	s_or_b64 exec, exec, s[10:11]
	s_waitcnt vmcnt(0) lgkmcnt(0)
	v_readfirstlane_b32 s2, v3
	v_mul_u32_u24_e32 v4, 6, v2
	v_mul_u32_u24_e32 v5, 6, v0
	s_add_u32 s2, s2, 1
	v_cmp_ne_u32_e32 vcc, s2, v4
	v_mov_b32_e32 v2, 0x583000
	v_readfirstlane_b32 s8, v5
	s_cbranch_vccnz .Lgb_poll_5
	buffer_wbl2 sc1
	v_mov_b32_e32 v3, 1
	s_waitcnt vmcnt(0)
	global_atomic_add v2, v3, s[72:73] offset:1024

; __device__ __forceinline__ unsigned xb_ld(unsigned* p)              { return __hip_atomic_load(p, __ATOMIC_RELAXED, __HIP_MEMORY_SCOPE_AGENT); }
; __device__ __forceinline__ unsigned xb_add(unsigned* p, unsigned v) { return __hip_atomic_fetch_add(p, v, __ATOMIC_RELAXED, __HIP_MEMORY_SCOPE_AGENT); }
; #define XB_SPIN(cond, bar) do { unsigned _sp = 0; while (cond) { __builtin_amdgcn_s_sleep(1); \
;     if ((++_sp & 255u) == 0u) { if (xb_ld(&(bar)[XB_TMO])) break; if (_sp > XB_SPIN_CAP) { atomicAdd(&(bar)[XB_TMO], 1u); break; } } } } while (0)
; __device__ __forceinline__ void xcd_barrier(const XcdBarrier& b) {
;     ...
;         unsigned nloc = b.st[0], nx = b.st[1];
;         if (nloc == 0u) { xcd_barrier_complete(bar, b.x, nloc, nx); b.st[0] = nloc; b.st[1] = nx; }
;         const unsigned old = xb_add(&bar[XB_XSUB(b.x)], 1u);
;         const unsigned gen = old / nloc;
;         if (old + 1u == (gen + 1u) * nloc) {
;             __builtin_amdgcn_fence(__ATOMIC_RELEASE, "agent");
;             asm volatile("s_waitcnt vmcnt(0)" ::: "memory");
;             const unsigned og = xb_add(&bar[XB_TOP], 1u);
;             const unsigned tg = og / nx;
;             if (og + 1u == (tg + 1u) * nx) xb_add(&bar[XB_TOPGEN], 1u);
;             else XB_SPIN(xb_ld(&bar[XB_TOPGEN]) == tg, bar);
;             __builtin_amdgcn_fence(__ATOMIC_ACQUIRE, "agent");
;             xb_add(&bar[XB_XGEN(b.x)], 1u);
;             asm volatile("s_waitcnt vmcnt(0)" ::: "memory");
;         } else {
;             XB_SPIN(xb_ld(&bar[XB_XGEN(b.x)]) == gen, bar);
.LBB0_1177:
	s_or_b64 exec, exec, s[8:9]
	s_waitcnt vmcnt(0) lgkmcnt(0)
	v_readfirstlane_b32 s2, v3
	v_mul_u32_u24_e32 v4, 7, v2
	v_mul_u32_u24_e32 v5, 7, v0
	s_add_u32 s2, s2, 1
	v_cmp_ne_u32_e32 vcc, s2, v4
	v_mov_b32_e32 v2, 0x583000
	v_readfirstlane_b32 s8, v5
	s_cbranch_vccnz .Lgb_poll_6
	buffer_wbl2 sc1
	v_mov_b32_e32 v3, 1
	s_waitcnt vmcnt(0)
	global_atomic_add v2, v3, s[72:73] offset:1024

; __device__ __forceinline__ unsigned xb_ld(unsigned* p)              { return __hip_atomic_load(p, __ATOMIC_RELAXED, __HIP_MEMORY_SCOPE_AGENT); }
; __device__ __forceinline__ unsigned xb_add(unsigned* p, unsigned v) { return __hip_atomic_fetch_add(p, v, __ATOMIC_RELAXED, __HIP_MEMORY_SCOPE_AGENT); }
; #define XB_SPIN(cond, bar) do { unsigned _sp = 0; while (cond) { __builtin_amdgcn_s_sleep(1); \
;     if ((++_sp & 255u) == 0u) { if (xb_ld(&(bar)[XB_TMO])) break; if (_sp > XB_SPIN_CAP) { atomicAdd(&(bar)[XB_TMO], 1u); break; } } } } while (0)
; __device__ __forceinline__ void xcd_barrier(const XcdBarrier& b) {
;     ...
;         unsigned nloc = b.st[0], nx = b.st[1];
;         if (nloc == 0u) { xcd_barrier_complete(bar, b.x, nloc, nx); b.st[0] = nloc; b.st[1] = nx; }
;         const unsigned old = xb_add(&bar[XB_XSUB(b.x)], 1u);
;         const unsigned gen = old / nloc;
;         if (old + 1u == (gen + 1u) * nloc) {
;             __builtin_amdgcn_fence(__ATOMIC_RELEASE, "agent");
;             asm volatile("s_waitcnt vmcnt(0)" ::: "memory");
;             const unsigned og = xb_add(&bar[XB_TOP], 1u);
;             const unsigned tg = og / nx;
;             if (og + 1u == (tg + 1u) * nx) xb_add(&bar[XB_TOPGEN], 1u);
;             else XB_SPIN(xb_ld(&bar[XB_TOPGEN]) == tg, bar);
;             __builtin_amdgcn_fence(__ATOMIC_ACQUIRE, "agent");
;             xb_add(&bar[XB_XGEN(b.x)], 1u);
;             asm volatile("s_waitcnt vmcnt(0)" ::: "memory");
;         } else {
;             XB_SPIN(xb_ld(&bar[XB_XGEN(b.x)]) == gen, bar);
.LBB0_1271:
	s_or_b64 exec, exec, s[8:9]
	s_waitcnt vmcnt(0) lgkmcnt(0)
	v_readfirstlane_b32 s2, v3
	v_mul_u32_u24_e32 v4, 8, v2
	v_mul_u32_u24_e32 v5, 8, v0
	s_add_u32 s2, s2, 1
	v_cmp_ne_u32_e32 vcc, s2, v4
	v_mov_b32_e32 v2, 0x583000
	v_readfirstlane_b32 s8, v5
	s_cbranch_vccnz .Lgb_poll_7
	buffer_wbl2 sc1
	v_mov_b32_e32 v3, 1
	s_waitcnt vmcnt(0)
	global_atomic_add v2, v3, s[72:73] offset:1024

; __device__ __forceinline__ unsigned xb_ld(unsigned* p)              { return __hip_atomic_load(p, __ATOMIC_RELAXED, __HIP_MEMORY_SCOPE_AGENT); }
; __device__ __forceinline__ unsigned xb_add(unsigned* p, unsigned v) { return __hip_atomic_fetch_add(p, v, __ATOMIC_RELAXED, __HIP_MEMORY_SCOPE_AGENT); }
; #define XB_SPIN(cond, bar) do { unsigned _sp = 0; while (cond) { __builtin_amdgcn_s_sleep(1); \
;     if ((++_sp & 255u) == 0u) { if (xb_ld(&(bar)[XB_TMO])) break; if (_sp > XB_SPIN_CAP) { atomicAdd(&(bar)[XB_TMO], 1u); break; } } } } while (0)
; __device__ __forceinline__ void xcd_barrier(const XcdBarrier& b) {
;     ...
;         unsigned nloc = b.st[0], nx = b.st[1];
;         if (nloc == 0u) { xcd_barrier_complete(bar, b.x, nloc, nx); b.st[0] = nloc; b.st[1] = nx; }
;         const unsigned old = xb_add(&bar[XB_XSUB(b.x)], 1u);
;         const unsigned gen = old / nloc;
;         if (old + 1u == (gen + 1u) * nloc) {
;             __builtin_amdgcn_fence(__ATOMIC_RELEASE, "agent");
;             asm volatile("s_waitcnt vmcnt(0)" ::: "memory");
;             const unsigned og = xb_add(&bar[XB_TOP], 1u);
;             const unsigned tg = og / nx;
;             if (og + 1u == (tg + 1u) * nx) xb_add(&bar[XB_TOPGEN], 1u);
;             else XB_SPIN(xb_ld(&bar[XB_TOPGEN]) == tg, bar);
;             __builtin_amdgcn_fence(__ATOMIC_ACQUIRE, "agent");
;             xb_add(&bar[XB_XGEN(b.x)], 1u);
;             asm volatile("s_waitcnt vmcnt(0)" ::: "memory");
;         } else {
;             XB_SPIN(xb_ld(&bar[XB_XGEN(b.x)]) == gen, bar);
.LBB0_1385:
	s_or_b64 exec, exec, s[8:9]
	s_waitcnt vmcnt(0) lgkmcnt(0)
	v_readfirstlane_b32 s2, v3
	v_mul_u32_u24_e32 v4, 9, v2
	v_mul_u32_u24_e32 v5, 9, v0
	s_add_u32 s2, s2, 1
	v_cmp_ne_u32_e32 vcc, s2, v4
	v_mov_b32_e32 v2, 0x583000
	v_readfirstlane_b32 s8, v5
	s_cbranch_vccnz .Lgb_poll_8
	buffer_wbl2 sc1
	v_mov_b32_e32 v3, 1
	s_waitcnt vmcnt(0)
	global_atomic_add v2, v3, s[72:73] offset:1024
